# two-level release; the XCC leader waits only for its top-counter atomic (vmcnt(1)), its L1 invalidate keeps flying
# baseline (speedup 1.0000x reference)
.Lcen_done:
	v_min_u32_e32 v2, 1, v2
	v_min_u32_e32 v3, 1, v3
	v_min_u32_e32 v4, 1, v4
	v_min_u32_e32 v5, 1, v5
	v_min_u32_e32 v6, 1, v6
	v_min_u32_e32 v7, 1, v7
	v_min_u32_e32 v8, 1, v8
	v_min_u32_e32 v9, 1, v9
	v_add_u32_e32 v1, v2, v3
	v_add_u32_e32 v1, v1, v4
	v_add_u32_e32 v1, v1, v5
	v_add_u32_e32 v1, v1, v6
	v_add_u32_e32 v1, v1, v7
	v_add_u32_e32 v1, v1, v8
	v_add_u32_e32 v1, v1, v9
	s_nop 0
	v_readfirstlane_b32 s101, v1
	s_getreg_b32 s5, hwreg(HW_REG_XCC_ID, 0, 4)
	s_lshl_b32 s5, s5, 8
	s_add_u32 s5, s5, 0x1000
	v_mov_b32_e32 v0, s5
	global_load_dword v1, v0, s[68:69] sc1
	s_waitcnt vmcnt(0)
	v_readfirstlane_b32 s98, v1
	s_nop 3
	s_sub_i32 s4, 1, s34
	s_getreg_b32 s5, hwreg(HW_REG_XCC_ID, 0, 4)
	s_mul_i32 s6, s98, s4
	s_lshl_b32 s5, s5, 8
	v_mov_b32_e32 v0, s5
	v_mov_b32_e32 v1, 1
	global_atomic_add v1, v0, v1, s[68:69] sc0
	s_mul_i32 s7, s101, s4
	s_add_u32 s5, s5, 0x1080
	s_waitcnt vmcnt(0)
	v_add_u32_e32 v1, 1, v1
	v_cmp_eq_u32_e32 vcc, s6, v1
	s_cbranch_vccz .Lgb_half_s0
	buffer_wbl2 sc1
	s_waitcnt vmcnt(0)
	v_mov_b32_e32 v0, 0
	v_mov_b32_e32 v1, 1
	global_atomic_add v1, v0, v1, s[14:15] sc0
	buffer_inv sc1
	s_waitcnt vmcnt(1)
	v_add_u32_e32 v1, 1, v1
	v_cmp_eq_u32_e32 vcc, s7, v1
	s_cbranch_vccnz .Lgb_rel_s0

.LBB0_151:
	s_cmp_lt_i32 s35, 3
	s_cbranch_scc1 .LBB0_160
	v_mbcnt_lo_u32_b32 v0, -1, 0
	v_mbcnt_hi_u32_b32 v0, -1, v0
	s_waitcnt vmcnt(0) lgkmcnt(0)
	s_waitcnt vmcnt(0) lgkmcnt(0)
	v_add_u32_e32 v0, s84, v0
	v_cmp_gt_u32_e32 vcc, 64, v0
	s_barrier
	s_and_saveexec_b64 s[0:1], vcc
	s_cbranch_execz .LBB0_159
	s_waitcnt vmcnt(0)
	v_cmp_eq_u32_e32 vcc, 0, v0
	s_and_saveexec_b64 s[2:3], vcc
	s_cbranch_execz .LBB0_158
	s_sub_i32 s4, 2, s34
	s_getreg_b32 s5, hwreg(HW_REG_XCC_ID, 0, 4)
	s_mul_i32 s6, s98, s4
	s_lshl_b32 s5, s5, 8
	v_mov_b32_e32 v0, s5
	v_mov_b32_e32 v1, 1
	global_atomic_add v1, v0, v1, s[68:69] sc0
	s_mul_i32 s7, s101, s4
	s_add_u32 s5, s5, 0x1080
	s_waitcnt vmcnt(0)
	v_add_u32_e32 v1, 1, v1
	v_cmp_eq_u32_e32 vcc, s6, v1
	s_cbranch_vccz .Lgb_half_s1
	buffer_wbl2 sc1
	s_waitcnt vmcnt(0)
	v_mov_b32_e32 v0, 0
	v_mov_b32_e32 v1, 1
	global_atomic_add v1, v0, v1, s[14:15] sc0
	buffer_inv sc1
	s_waitcnt vmcnt(1)
	v_add_u32_e32 v1, 1, v1
	v_cmp_eq_u32_e32 vcc, s7, v1
	s_cbranch_vccnz .Lgb_rel_s1

.LBB0_211:
	s_cmp_eq_u32 s100, 1
	s_cbranch_scc1 .Ldil_ret12
	s_cmp_lt_i32 s35, 4
	s_cbranch_scc1 .LBB0_220
	v_mbcnt_lo_u32_b32 v0, -1, 0
	v_mbcnt_hi_u32_b32 v0, -1, v0
	s_waitcnt vmcnt(0) lgkmcnt(0)
	s_waitcnt lgkmcnt(0)
	v_add_u32_e32 v0, s84, v0
	v_cmp_gt_u32_e32 vcc, 64, v0
	s_barrier
	s_and_saveexec_b64 s[0:1], vcc
	s_cbranch_execz .LBB0_219
	s_waitcnt vmcnt(0)
	s_waitcnt vmcnt(0)
	v_cmp_eq_u32_e32 vcc, 0, v0
	s_and_saveexec_b64 s[2:3], vcc
	s_cbranch_execz .LBB0_218
	s_sub_i32 s4, 3, s34
	s_getreg_b32 s5, hwreg(HW_REG_XCC_ID, 0, 4)
	s_mul_i32 s6, s98, s4
	s_lshl_b32 s5, s5, 8
	v_mov_b32_e32 v0, s5
	v_mov_b32_e32 v1, 1
	global_atomic_add v1, v0, v1, s[68:69] sc0
	s_mul_i32 s7, s101, s4
	s_add_u32 s5, s5, 0x1080
	s_waitcnt vmcnt(0)
	v_add_u32_e32 v1, 1, v1
	v_cmp_eq_u32_e32 vcc, s6, v1
	s_cbranch_vccz .Lgb_half_s2
	buffer_wbl2 sc1
	s_waitcnt vmcnt(0)
	v_mov_b32_e32 v0, 0
	v_mov_b32_e32 v1, 1
	global_atomic_add v1, v0, v1, s[14:15] sc0
	buffer_inv sc1
	s_waitcnt vmcnt(1)
	v_add_u32_e32 v1, 1, v1
	v_cmp_eq_u32_e32 vcc, s7, v1
	s_cbranch_vccnz .Lgb_rel_s2

.LBB0_245:
	s_cmp_lt_i32 s35, 5
	s_cbranch_scc1 .LBB0_254
	v_mbcnt_lo_u32_b32 v0, -1, 0
	v_mbcnt_hi_u32_b32 v0, -1, v0
	s_waitcnt vmcnt(0) lgkmcnt(0)
	s_waitcnt vmcnt(0) lgkmcnt(0)
	v_add_u32_e32 v0, s84, v0
	v_cmp_gt_u32_e32 vcc, 64, v0
	s_barrier
	s_and_saveexec_b64 s[0:1], vcc
	s_cbranch_execz .LBB0_253
	s_waitcnt vmcnt(0)
	v_cmp_eq_u32_e32 vcc, 0, v0
	s_and_saveexec_b64 s[2:3], vcc
	s_cbranch_execz .LBB0_252
	s_sub_i32 s4, 4, s34
	s_getreg_b32 s5, hwreg(HW_REG_XCC_ID, 0, 4)
	s_mul_i32 s6, s98, s4
	s_lshl_b32 s5, s5, 8
	v_mov_b32_e32 v0, s5
	v_mov_b32_e32 v1, 1
	global_atomic_add v1, v0, v1, s[68:69] sc0
	s_mul_i32 s7, s101, s4
	s_add_u32 s5, s5, 0x1080
	s_waitcnt vmcnt(0)
	v_add_u32_e32 v1, 1, v1
	v_cmp_eq_u32_e32 vcc, s6, v1
	s_cbranch_vccz .Lgb_half_s3
	buffer_wbl2 sc1
	s_waitcnt vmcnt(0)
	v_mov_b32_e32 v0, 0
	v_mov_b32_e32 v1, 1
	global_atomic_add v1, v0, v1, s[14:15] sc0
	buffer_inv sc1
	s_waitcnt vmcnt(1)
	v_add_u32_e32 v1, 1, v1
	v_cmp_eq_u32_e32 vcc, s7, v1
	s_cbranch_vccnz .Lgb_rel_s3

.LBB0_289:
	s_cmp_eq_u32 s99, 1
	s_cbranch_scc1 .Lmla_ret14
	s_cmp_lt_i32 s35, 6
	s_cbranch_scc1 .LBB0_298
	v_mbcnt_lo_u32_b32 v0, -1, 0
	v_mbcnt_hi_u32_b32 v0, -1, v0
	s_waitcnt vmcnt(0) lgkmcnt(0)
	s_waitcnt lgkmcnt(0)
	v_add_u32_e32 v0, s84, v0
	v_cmp_gt_u32_e32 vcc, 64, v0
	s_barrier
	s_and_saveexec_b64 s[0:1], vcc
	s_cbranch_execz .LBB0_297
	s_waitcnt vmcnt(0)
	s_waitcnt vmcnt(0)
	v_cmp_eq_u32_e32 vcc, 0, v0
	s_and_saveexec_b64 s[2:3], vcc
	s_cbranch_execz .LBB0_296
	s_sub_i32 s4, 5, s34
	s_getreg_b32 s5, hwreg(HW_REG_XCC_ID, 0, 4)
	s_mul_i32 s6, s98, s4
	s_lshl_b32 s5, s5, 8
	v_mov_b32_e32 v0, s5
	v_mov_b32_e32 v1, 1
	global_atomic_add v1, v0, v1, s[68:69] sc0
	s_mul_i32 s7, s101, s4
	s_add_u32 s5, s5, 0x1080
	s_waitcnt vmcnt(0)
	v_add_u32_e32 v1, 1, v1
	v_cmp_eq_u32_e32 vcc, s6, v1
	s_cbranch_vccz .Lgb_half_s4
	buffer_wbl2 sc1
	s_waitcnt vmcnt(0)
	v_mov_b32_e32 v0, 0
	v_mov_b32_e32 v1, 1
	global_atomic_add v1, v0, v1, s[14:15] sc0
	buffer_inv sc1
	s_waitcnt vmcnt(1)
	v_add_u32_e32 v1, 1, v1
	v_cmp_eq_u32_e32 vcc, s7, v1
	s_cbranch_vccnz .Lgb_rel_s4

.LBB0_302:
	s_or_b64 exec, exec, s[2:3]
	s_cmp_lt_u32 s35, 7
	s_cbranch_scc1 .LBB0_311
	v_mbcnt_lo_u32_b32 v0, -1, 0
	v_mbcnt_hi_u32_b32 v0, -1, v0
	s_waitcnt vmcnt(0) lgkmcnt(0)
	s_waitcnt lgkmcnt(0)
	v_add_u32_e32 v0, s84, v0
	v_cmp_gt_u32_e32 vcc, 64, v0
	s_barrier
	s_and_saveexec_b64 s[0:1], vcc
	s_cbranch_execz .LBB0_310
	s_waitcnt vmcnt(0)
	s_waitcnt vmcnt(0)
	v_cmp_eq_u32_e32 vcc, 0, v0
	s_and_saveexec_b64 s[2:3], vcc
	s_cbranch_execz .LBB0_309
	s_sub_i32 s4, 6, s34
	s_getreg_b32 s5, hwreg(HW_REG_XCC_ID, 0, 4)
	s_mul_i32 s6, s98, s4
	s_lshl_b32 s5, s5, 8
	v_mov_b32_e32 v0, s5
	v_mov_b32_e32 v1, 1
	global_atomic_add v1, v0, v1, s[68:69] sc0
	s_mul_i32 s7, s101, s4
	s_add_u32 s5, s5, 0x1080
	s_waitcnt vmcnt(0)
	v_add_u32_e32 v1, 1, v1
	v_cmp_eq_u32_e32 vcc, s6, v1
	s_cbranch_vccz .Lgb_half_s5
	buffer_wbl2 sc1
	s_waitcnt vmcnt(0)
	v_mov_b32_e32 v0, 0
	v_mov_b32_e32 v1, 1
	global_atomic_add v1, v0, v1, s[14:15] sc0
	buffer_inv sc1
	s_waitcnt vmcnt(1)
	v_add_u32_e32 v1, 1, v1
	v_cmp_eq_u32_e32 vcc, s7, v1
	s_cbranch_vccnz .Lgb_rel_s5

.LBB0_327:
	s_cmp_lt_i32 s35, 8
	s_cbranch_scc1 .LBB0_336
	v_mbcnt_lo_u32_b32 v0, -1, 0
	v_mbcnt_hi_u32_b32 v0, -1, v0
	s_waitcnt vmcnt(0) lgkmcnt(0)
	s_waitcnt vmcnt(0) lgkmcnt(0)
	v_add_u32_e32 v0, s84, v0
	v_cmp_gt_u32_e32 vcc, 64, v0
	s_barrier
	s_and_saveexec_b64 s[0:1], vcc
	s_cbranch_execz .LBB0_335
	s_waitcnt vmcnt(0)
	v_cmp_eq_u32_e32 vcc, 0, v0
	s_and_saveexec_b64 s[2:3], vcc
	s_cbranch_execz .LBB0_334
	s_sub_i32 s4, 7, s34
	s_getreg_b32 s5, hwreg(HW_REG_XCC_ID, 0, 4)
	s_mul_i32 s6, s98, s4
	s_lshl_b32 s5, s5, 8
	v_mov_b32_e32 v0, s5
	v_mov_b32_e32 v1, 1
	global_atomic_add v1, v0, v1, s[68:69] sc0
	s_mul_i32 s7, s101, s4
	s_add_u32 s5, s5, 0x1080
	s_waitcnt vmcnt(0)
	v_add_u32_e32 v1, 1, v1
	v_cmp_eq_u32_e32 vcc, s6, v1
	s_cbranch_vccz .Lgb_half_s6
	buffer_wbl2 sc1
	s_waitcnt vmcnt(0)
	v_mov_b32_e32 v0, 0
	v_mov_b32_e32 v1, 1
	global_atomic_add v1, v0, v1, s[14:15] sc0
	buffer_inv sc1
	s_waitcnt vmcnt(1)
	v_add_u32_e32 v1, 1, v1
	v_cmp_eq_u32_e32 vcc, s7, v1
	s_cbranch_vccnz .Lgb_rel_s6

.LBB0_348:
	s_or_b64 exec, exec, s[2:3]
	s_cmp_lt_i32 s35, 9
	s_cbranch_scc1 .LBB0_357
	v_mbcnt_lo_u32_b32 v0, -1, 0
	v_mbcnt_hi_u32_b32 v0, -1, v0
	s_waitcnt vmcnt(0) lgkmcnt(0)
	s_waitcnt lgkmcnt(0)
	v_add_u32_e32 v0, s84, v0
	v_cmp_gt_u32_e32 vcc, 64, v0
	s_barrier
	s_and_saveexec_b64 s[0:1], vcc
	s_cbranch_execz .LBB0_356
	s_waitcnt vmcnt(0)
	s_waitcnt vmcnt(0)
	v_cmp_eq_u32_e32 vcc, 0, v0
	s_and_saveexec_b64 s[2:3], vcc
	s_cbranch_execz .LBB0_355
	s_sub_i32 s4, 8, s34
	s_getreg_b32 s5, hwreg(HW_REG_XCC_ID, 0, 4)
	s_mul_i32 s6, s98, s4
	s_lshl_b32 s5, s5, 8
	v_mov_b32_e32 v0, s5
	v_mov_b32_e32 v1, 1
	global_atomic_add v1, v0, v1, s[68:69] sc0
	s_mul_i32 s7, s101, s4
	s_add_u32 s5, s5, 0x1080
	s_waitcnt vmcnt(0)
	v_add_u32_e32 v1, 1, v1
	v_cmp_eq_u32_e32 vcc, s6, v1
	s_cbranch_vccz .Lgb_half_s7
	buffer_wbl2 sc1
	s_waitcnt vmcnt(0)
	v_mov_b32_e32 v0, 0
	v_mov_b32_e32 v1, 1
	global_atomic_add v1, v0, v1, s[14:15] sc0
	buffer_inv sc1
	s_waitcnt vmcnt(1)
	v_add_u32_e32 v1, 1, v1
	v_cmp_eq_u32_e32 vcc, s7, v1
	s_cbranch_vccnz .Lgb_rel_s7

.LBB0_373:
	s_cmp_lt_i32 s35, 10
	s_cbranch_scc1 .LBB0_382
	v_mbcnt_lo_u32_b32 v0, -1, 0
	v_mbcnt_hi_u32_b32 v0, -1, v0
	s_waitcnt vmcnt(0) lgkmcnt(0)
	s_waitcnt vmcnt(0) lgkmcnt(0)
	v_add_u32_e32 v0, s84, v0
	v_cmp_gt_u32_e32 vcc, 64, v0
	s_barrier
	s_and_saveexec_b64 s[0:1], vcc
	s_cbranch_execz .LBB0_381
	s_waitcnt vmcnt(0)
	v_cmp_eq_u32_e32 vcc, 0, v0
	s_and_saveexec_b64 s[2:3], vcc
	s_cbranch_execz .LBB0_380
	s_sub_i32 s4, 9, s34
	s_getreg_b32 s5, hwreg(HW_REG_XCC_ID, 0, 4)
	s_mul_i32 s6, s98, s4
	s_lshl_b32 s5, s5, 8
	v_mov_b32_e32 v0, s5
	v_mov_b32_e32 v1, 1
	global_atomic_add v1, v0, v1, s[68:69] sc0
	s_mul_i32 s7, s101, s4
	s_add_u32 s5, s5, 0x1080
	s_waitcnt vmcnt(0)
	v_add_u32_e32 v1, 1, v1
	v_cmp_eq_u32_e32 vcc, s6, v1
	s_cbranch_vccz .Lgb_half_s8
	buffer_wbl2 sc1
	s_waitcnt vmcnt(0)
	v_mov_b32_e32 v0, 0
	v_mov_b32_e32 v1, 1
	global_atomic_add v1, v0, v1, s[14:15] sc0
	buffer_inv sc1
	s_waitcnt vmcnt(1)
	v_add_u32_e32 v1, 1, v1
	v_cmp_eq_u32_e32 vcc, s7, v1
	s_cbranch_vccnz .Lgb_rel_s8

.LBB0_398:
	s_cmp_lt_i32 s35, 11
	s_cbranch_scc1 .LBB0_407
	v_mbcnt_lo_u32_b32 v0, -1, 0
	v_mbcnt_hi_u32_b32 v0, -1, v0
	s_waitcnt vmcnt(0) lgkmcnt(0)
	s_waitcnt vmcnt(0) lgkmcnt(0)
	v_add_u32_e32 v0, s84, v0
	v_cmp_gt_u32_e32 vcc, 64, v0
	s_barrier
	s_and_saveexec_b64 s[0:1], vcc
	s_cbranch_execz .LBB0_406
	s_waitcnt vmcnt(0)
	v_cmp_eq_u32_e32 vcc, 0, v0
	s_and_saveexec_b64 s[2:3], vcc
	s_cbranch_execz .LBB0_405
	s_sub_i32 s4, 10, s34
	s_getreg_b32 s5, hwreg(HW_REG_XCC_ID, 0, 4)
	s_mul_i32 s6, s98, s4
	s_lshl_b32 s5, s5, 8
	v_mov_b32_e32 v0, s5
	v_mov_b32_e32 v1, 1
	global_atomic_add v1, v0, v1, s[68:69] sc0
	s_mul_i32 s7, s101, s4
	s_add_u32 s5, s5, 0x1080
	s_waitcnt vmcnt(0)
	v_add_u32_e32 v1, 1, v1
	v_cmp_eq_u32_e32 vcc, s6, v1
	s_cbranch_vccz .Lgb_half_s9
	buffer_wbl2 sc1
	s_waitcnt vmcnt(0)
	v_mov_b32_e32 v0, 0
	v_mov_b32_e32 v1, 1
	global_atomic_add v1, v0, v1, s[14:15] sc0
	buffer_inv sc1
	s_waitcnt vmcnt(1)
	v_add_u32_e32 v1, 1, v1
	v_cmp_eq_u32_e32 vcc, s7, v1
	s_cbranch_vccnz .Lgb_rel_s9

.LBB0_442:
	s_or_b64 exec, exec, s[0:1]
	s_cmp_lt_i32 s35, 12
	s_cbranch_scc1 .LBB0_451
	v_mbcnt_lo_u32_b32 v0, -1, 0
	v_mbcnt_hi_u32_b32 v0, -1, v0
	s_waitcnt vmcnt(0) lgkmcnt(0)
	s_waitcnt lgkmcnt(0)
	v_add_u32_e32 v0, s84, v0
	v_cmp_gt_u32_e32 vcc, 64, v0
	s_barrier
	s_and_saveexec_b64 s[0:1], vcc
	s_cbranch_execz .LBB0_450
	s_waitcnt vmcnt(0)
	s_waitcnt vmcnt(0)
	v_cmp_eq_u32_e32 vcc, 0, v0
	s_and_saveexec_b64 s[2:3], vcc
	s_cbranch_execz .LBB0_449
	s_sub_i32 s4, 11, s34
	s_getreg_b32 s5, hwreg(HW_REG_XCC_ID, 0, 4)
	s_mul_i32 s6, s98, s4
	s_lshl_b32 s5, s5, 8
	v_mov_b32_e32 v0, s5
	v_mov_b32_e32 v1, 1
	global_atomic_add v1, v0, v1, s[68:69] sc0
	s_mul_i32 s7, s101, s4
	s_add_u32 s5, s5, 0x1080
	s_waitcnt vmcnt(0)
	v_add_u32_e32 v1, 1, v1
	v_cmp_eq_u32_e32 vcc, s6, v1
	s_cbranch_vccz .Lgb_half_s10
	buffer_wbl2 sc1
	s_waitcnt vmcnt(0)
	v_mov_b32_e32 v0, 0
	v_mov_b32_e32 v1, 1
	global_atomic_add v1, v0, v1, s[14:15] sc0
	buffer_inv sc1
	s_waitcnt vmcnt(1)
	v_add_u32_e32 v1, 1, v1
	v_cmp_eq_u32_e32 vcc, s7, v1
	s_cbranch_vccnz .Lgb_rel_s10

.LBB0_531:
	s_cmp_lt_i32 s35, 13
	s_cbranch_scc1 .LBB0_540
	v_mbcnt_lo_u32_b32 v0, -1, 0
	v_mbcnt_hi_u32_b32 v0, -1, v0
	s_waitcnt vmcnt(0) lgkmcnt(0)
	s_waitcnt vmcnt(0) lgkmcnt(0)
	v_add_u32_e32 v0, s84, v0
	v_cmp_gt_u32_e32 vcc, 64, v0
	s_barrier
	s_and_saveexec_b64 s[0:1], vcc
	s_cbranch_execz .LBB0_539
	s_waitcnt vmcnt(0)
	v_cmp_eq_u32_e32 vcc, 0, v0
	s_and_saveexec_b64 s[2:3], vcc
	s_cbranch_execz .LBB0_538
	s_sub_i32 s4, 12, s34
	s_getreg_b32 s5, hwreg(HW_REG_XCC_ID, 0, 4)
	s_mul_i32 s6, s98, s4
	s_lshl_b32 s5, s5, 8
	v_mov_b32_e32 v0, s5
	v_mov_b32_e32 v1, 1
	global_atomic_add v1, v0, v1, s[68:69] sc0
	s_mul_i32 s7, s101, s4
	s_add_u32 s5, s5, 0x1080
	s_waitcnt vmcnt(0)
	v_add_u32_e32 v1, 1, v1
	v_cmp_eq_u32_e32 vcc, s6, v1
	s_cbranch_vccz .Lgb_half_s11
	buffer_wbl2 sc1
	s_waitcnt vmcnt(0)
	v_mov_b32_e32 v0, 0
	v_mov_b32_e32 v1, 1
	global_atomic_add v1, v0, v1, s[14:15] sc0
	buffer_inv sc1
	s_waitcnt vmcnt(1)
	v_add_u32_e32 v1, 1, v1
	v_cmp_eq_u32_e32 vcc, s7, v1
	s_cbranch_vccnz .Lgb_rel_s11

.Ldil_ret12:
.LBB0_590:
	s_cmp_lt_i32 s35, 14
	s_cbranch_scc1 .LBB0_599
	v_mbcnt_lo_u32_b32 v0, -1, 0
	v_mbcnt_hi_u32_b32 v0, -1, v0
	s_waitcnt vmcnt(0) lgkmcnt(0)
	s_waitcnt lgkmcnt(0)
	v_add_u32_e32 v0, s84, v0
	v_cmp_gt_u32_e32 vcc, 64, v0
	s_barrier
	s_and_saveexec_b64 s[0:1], vcc
	s_cbranch_execz .LBB0_598
	s_waitcnt vmcnt(0)
	s_waitcnt vmcnt(0)
	v_cmp_eq_u32_e32 vcc, 0, v0
	s_and_saveexec_b64 s[2:3], vcc
	s_cbranch_execz .LBB0_597
	s_sub_i32 s4, 13, s34
	s_getreg_b32 s5, hwreg(HW_REG_XCC_ID, 0, 4)
	s_mul_i32 s6, s98, s4
	s_lshl_b32 s5, s5, 8
	v_mov_b32_e32 v0, s5
	v_mov_b32_e32 v1, 1
	global_atomic_add v1, v0, v1, s[68:69] sc0
	s_mul_i32 s7, s101, s4
	s_add_u32 s5, s5, 0x1080
	s_waitcnt vmcnt(0)
	v_add_u32_e32 v1, 1, v1
	v_cmp_eq_u32_e32 vcc, s6, v1
	s_cbranch_vccz .Lgb_half_s12
	buffer_wbl2 sc1
	s_waitcnt vmcnt(0)
	v_mov_b32_e32 v0, 0
	v_mov_b32_e32 v1, 1
	global_atomic_add v1, v0, v1, s[14:15] sc0
	buffer_inv sc1
	s_waitcnt vmcnt(1)
	v_add_u32_e32 v1, 1, v1
	v_cmp_eq_u32_e32 vcc, s7, v1
	s_cbranch_vccnz .Lgb_rel_s12

.LBB0_624:
	s_cmp_lt_i32 s35, 15
	s_cbranch_scc1 .LBB0_633
	v_mbcnt_lo_u32_b32 v0, -1, 0
	v_mbcnt_hi_u32_b32 v0, -1, v0
	s_waitcnt vmcnt(0) lgkmcnt(0)
	s_waitcnt vmcnt(0) lgkmcnt(0)
	v_add_u32_e32 v0, s84, v0
	v_cmp_gt_u32_e32 vcc, 64, v0
	s_barrier
	s_and_saveexec_b64 s[0:1], vcc
	s_cbranch_execz .LBB0_632
	s_waitcnt vmcnt(0)
	v_cmp_eq_u32_e32 vcc, 0, v0
	s_and_saveexec_b64 s[2:3], vcc
	s_cbranch_execz .LBB0_631
	s_sub_i32 s4, 14, s34
	s_getreg_b32 s5, hwreg(HW_REG_XCC_ID, 0, 4)
	s_mul_i32 s6, s98, s4
	s_lshl_b32 s5, s5, 8
	v_mov_b32_e32 v0, s5
	v_mov_b32_e32 v1, 1
	global_atomic_add v1, v0, v1, s[68:69] sc0
	s_mul_i32 s7, s101, s4
	s_add_u32 s5, s5, 0x1080
	s_waitcnt vmcnt(0)
	v_add_u32_e32 v1, 1, v1
	v_cmp_eq_u32_e32 vcc, s6, v1
	s_cbranch_vccz .Lgb_half_s13
	buffer_wbl2 sc1
	s_waitcnt vmcnt(0)
	v_mov_b32_e32 v0, 0
	v_mov_b32_e32 v1, 1
	global_atomic_add v1, v0, v1, s[14:15] sc0
	buffer_inv sc1
	s_waitcnt vmcnt(1)
	v_add_u32_e32 v1, 1, v1
	v_cmp_eq_u32_e32 vcc, s7, v1
	s_cbranch_vccnz .Lgb_rel_s13

.Lmla_ret14:
.LBB0_668:
	s_cmp_lt_i32 s35, 16
	s_cbranch_scc1 .LBB0_677
	v_mbcnt_lo_u32_b32 v0, -1, 0
	v_mbcnt_hi_u32_b32 v0, -1, v0
	s_waitcnt vmcnt(0) lgkmcnt(0)
	s_waitcnt lgkmcnt(0)
	v_add_u32_e32 v0, s84, v0
	v_cmp_gt_u32_e32 vcc, 64, v0
	s_barrier
	s_and_saveexec_b64 s[0:1], vcc
	s_cbranch_execz .LBB0_676
	s_waitcnt vmcnt(0)
	s_waitcnt vmcnt(0)
	v_cmp_eq_u32_e32 vcc, 0, v0
	s_and_saveexec_b64 s[2:3], vcc
	s_cbranch_execz .LBB0_675
	s_sub_i32 s4, 15, s34
	s_getreg_b32 s5, hwreg(HW_REG_XCC_ID, 0, 4)
	s_mul_i32 s6, s98, s4
	s_lshl_b32 s5, s5, 8
	v_mov_b32_e32 v0, s5
	v_mov_b32_e32 v1, 1
	global_atomic_add v1, v0, v1, s[68:69] sc0
	s_mul_i32 s7, s101, s4
	s_add_u32 s5, s5, 0x1080
	s_waitcnt vmcnt(0)
	v_add_u32_e32 v1, 1, v1
	v_cmp_eq_u32_e32 vcc, s6, v1
	s_cbranch_vccz .Lgb_half_s14
	buffer_wbl2 sc1
	s_waitcnt vmcnt(0)
	v_mov_b32_e32 v0, 0
	v_mov_b32_e32 v1, 1
	global_atomic_add v1, v0, v1, s[14:15] sc0
	buffer_inv sc1
	s_waitcnt vmcnt(1)
	v_add_u32_e32 v1, 1, v1
	v_cmp_eq_u32_e32 vcc, s7, v1
	s_cbranch_vccnz .Lgb_rel_s14

.LBB0_681:
	s_or_b64 exec, exec, s[2:3]
	s_cmp_lt_u32 s35, 17
	s_cbranch_scc1 .LBB0_690
	v_mbcnt_lo_u32_b32 v0, -1, 0
	v_mbcnt_hi_u32_b32 v0, -1, v0
	s_waitcnt vmcnt(0) lgkmcnt(0)
	s_waitcnt lgkmcnt(0)
	v_add_u32_e32 v0, s84, v0
	v_cmp_gt_u32_e32 vcc, 64, v0
	s_barrier
	s_and_saveexec_b64 s[0:1], vcc
	s_cbranch_execz .LBB0_689
	s_waitcnt vmcnt(0)
	s_waitcnt vmcnt(0)
	v_cmp_eq_u32_e32 vcc, 0, v0
	s_and_saveexec_b64 s[2:3], vcc
	s_cbranch_execz .LBB0_688
	s_sub_i32 s4, 16, s34
	s_getreg_b32 s5, hwreg(HW_REG_XCC_ID, 0, 4)
	s_mul_i32 s6, s98, s4
	s_lshl_b32 s5, s5, 8
	v_mov_b32_e32 v0, s5
	v_mov_b32_e32 v1, 1
	global_atomic_add v1, v0, v1, s[68:69] sc0
	s_mul_i32 s7, s101, s4
	s_add_u32 s5, s5, 0x1080
	s_waitcnt vmcnt(0)
	v_add_u32_e32 v1, 1, v1
	v_cmp_eq_u32_e32 vcc, s6, v1
	s_cbranch_vccz .Lgb_half_s15
	buffer_wbl2 sc1
	s_waitcnt vmcnt(0)
	v_mov_b32_e32 v0, 0
	v_mov_b32_e32 v1, 1
	global_atomic_add v1, v0, v1, s[14:15] sc0
	buffer_inv sc1
	s_waitcnt vmcnt(1)
	v_add_u32_e32 v1, 1, v1
	v_cmp_eq_u32_e32 vcc, s7, v1
	s_cbranch_vccnz .Lgb_rel_s15

.LBB0_706:
	s_cmp_lt_i32 s35, 18
	s_cbranch_scc1 .LBB0_715
	v_mbcnt_lo_u32_b32 v0, -1, 0
	v_mbcnt_hi_u32_b32 v0, -1, v0
	s_waitcnt vmcnt(0) lgkmcnt(0)
	s_waitcnt vmcnt(0) lgkmcnt(0)
	v_add_u32_e32 v0, s84, v0
	v_cmp_gt_u32_e32 vcc, 64, v0
	s_barrier
	s_and_saveexec_b64 s[0:1], vcc
	s_cbranch_execz .LBB0_714
	s_waitcnt vmcnt(0)
	v_cmp_eq_u32_e32 vcc, 0, v0
	s_and_saveexec_b64 s[2:3], vcc
	s_cbranch_execz .LBB0_713
	s_sub_i32 s4, 17, s34
	s_getreg_b32 s5, hwreg(HW_REG_XCC_ID, 0, 4)
	s_mul_i32 s6, s98, s4
	s_lshl_b32 s5, s5, 8
	v_mov_b32_e32 v0, s5
	v_mov_b32_e32 v1, 1
	global_atomic_add v1, v0, v1, s[68:69] sc0
	s_mul_i32 s7, s101, s4
	s_add_u32 s5, s5, 0x1080
	s_waitcnt vmcnt(0)
	v_add_u32_e32 v1, 1, v1
	v_cmp_eq_u32_e32 vcc, s6, v1
	s_cbranch_vccz .Lgb_half_s16
	buffer_wbl2 sc1
	s_waitcnt vmcnt(0)
	v_mov_b32_e32 v0, 0
	v_mov_b32_e32 v1, 1
	global_atomic_add v1, v0, v1, s[14:15] sc0
	buffer_inv sc1
	s_waitcnt vmcnt(1)
	v_add_u32_e32 v1, 1, v1
	v_cmp_eq_u32_e32 vcc, s7, v1
	s_cbranch_vccnz .Lgb_rel_s16

.LBB0_719:
	s_or_b64 exec, exec, s[0:1]
	s_cmp_lt_u32 s35, 19
	s_cbranch_scc1 .LBB0_728
	v_mbcnt_lo_u32_b32 v0, -1, 0
	v_mbcnt_hi_u32_b32 v0, -1, v0
	s_waitcnt vmcnt(0) lgkmcnt(0)
	s_nop 0
	v_add_u32_e32 v0, s84, v0
	v_cmp_gt_u32_e32 vcc, 64, v0
	s_barrier
	s_and_saveexec_b64 s[0:1], vcc
	s_cbranch_execz .LBB0_727
	s_waitcnt vmcnt(0)
	s_waitcnt vmcnt(0)
	v_cmp_eq_u32_e32 vcc, 0, v0
	s_and_saveexec_b64 s[2:3], vcc
	s_cbranch_execz .LBB0_726
	s_sub_i32 s4, 18, s34
	s_getreg_b32 s5, hwreg(HW_REG_XCC_ID, 0, 4)
	s_mul_i32 s6, s98, s4
	s_lshl_b32 s5, s5, 8
	v_mov_b32_e32 v0, s5
	v_mov_b32_e32 v1, 1
	global_atomic_add v1, v0, v1, s[68:69] sc0
	s_mul_i32 s7, s101, s4
	s_add_u32 s5, s5, 0x1080
	s_waitcnt vmcnt(0)
	v_add_u32_e32 v1, 1, v1
	v_cmp_eq_u32_e32 vcc, s6, v1
	s_cbranch_vccz .Lgb_half_s17
	buffer_wbl2 sc1
	s_waitcnt vmcnt(0)
	v_mov_b32_e32 v0, 0
	v_mov_b32_e32 v1, 1
	global_atomic_add v1, v0, v1, s[14:15] sc0
	buffer_inv sc1
	s_waitcnt vmcnt(1)
	v_add_u32_e32 v1, 1, v1
	v_cmp_eq_u32_e32 vcc, s7, v1
	s_cbranch_vccnz .Lgb_rel_s17

.LBB0_744:
	s_cmp_lt_i32 s35, 20
	s_cbranch_scc1 .LBB0_753
	v_mbcnt_lo_u32_b32 v0, -1, 0
	v_mbcnt_hi_u32_b32 v0, -1, v0
	s_waitcnt vmcnt(0) lgkmcnt(0)
	s_waitcnt vmcnt(0) lgkmcnt(0)
	v_add_u32_e32 v0, s84, v0
	v_cmp_gt_u32_e32 vcc, 64, v0
	s_barrier
	s_and_saveexec_b64 s[0:1], vcc
	s_cbranch_execz .LBB0_752
	s_waitcnt vmcnt(0)
	v_cmp_eq_u32_e32 vcc, 0, v0
	s_and_saveexec_b64 s[2:3], vcc
	s_cbranch_execz .LBB0_751
	s_sub_i32 s4, 19, s34
	s_getreg_b32 s5, hwreg(HW_REG_XCC_ID, 0, 4)
	s_mul_i32 s6, s98, s4
	s_lshl_b32 s5, s5, 8
	v_mov_b32_e32 v0, s5
	v_mov_b32_e32 v1, 1
	global_atomic_add v1, v0, v1, s[68:69] sc0
	s_mul_i32 s7, s101, s4
	s_add_u32 s5, s5, 0x1080
	s_waitcnt vmcnt(0)
	v_add_u32_e32 v1, 1, v1
	v_cmp_eq_u32_e32 vcc, s6, v1
	s_cbranch_vccz .Lgb_half_s18
	buffer_wbl2 sc1
	s_waitcnt vmcnt(0)
	v_mov_b32_e32 v0, 0
	v_mov_b32_e32 v1, 1
	global_atomic_add v1, v0, v1, s[14:15] sc0
	buffer_inv sc1
	s_waitcnt vmcnt(1)
	v_add_u32_e32 v1, 1, v1
	v_cmp_eq_u32_e32 vcc, s7, v1
	s_cbranch_vccnz .Lgb_rel_s18

.LBB0_769:
	s_cmp_lt_i32 s35, 21
	s_cbranch_scc1 .LBB0_778
	v_mbcnt_lo_u32_b32 v0, -1, 0
	v_mbcnt_hi_u32_b32 v0, -1, v0
	s_waitcnt vmcnt(0) lgkmcnt(0)
	s_waitcnt vmcnt(0) lgkmcnt(0)
	v_add_u32_e32 v0, s84, v0
	v_cmp_gt_u32_e32 vcc, 64, v0
	s_barrier
	s_and_saveexec_b64 s[0:1], vcc
	s_cbranch_execz .LBB0_777
	s_waitcnt vmcnt(0)
	v_cmp_eq_u32_e32 vcc, 0, v0
	s_and_saveexec_b64 s[2:3], vcc
	s_cbranch_execz .LBB0_776
	s_sub_i32 s4, 20, s34
	s_getreg_b32 s5, hwreg(HW_REG_XCC_ID, 0, 4)
	s_mul_i32 s6, s98, s4
	s_lshl_b32 s5, s5, 8
	v_mov_b32_e32 v0, s5
	v_mov_b32_e32 v1, 1
	global_atomic_add v1, v0, v1, s[68:69] sc0
	s_mul_i32 s7, s101, s4
	s_add_u32 s5, s5, 0x1080
	s_waitcnt vmcnt(0)
	v_add_u32_e32 v1, 1, v1
	v_cmp_eq_u32_e32 vcc, s6, v1
	s_cbranch_vccz .Lgb_half_s19
	buffer_wbl2 sc1
	s_waitcnt vmcnt(0)
	v_mov_b32_e32 v0, 0
	v_mov_b32_e32 v1, 1
	global_atomic_add v1, v0, v1, s[14:15] sc0
	buffer_inv sc1
	s_waitcnt vmcnt(1)
	v_add_u32_e32 v1, 1, v1
	v_cmp_eq_u32_e32 vcc, s7, v1
	s_cbranch_vccnz .Lgb_rel_s19

.LBB0_782:
	s_or_b64 exec, exec, s[0:1]
	s_cmp_lt_u32 s35, 22
	s_cbranch_scc1 .LBB0_791
	v_mbcnt_lo_u32_b32 v0, -1, 0
	v_mbcnt_hi_u32_b32 v0, -1, v0
	s_waitcnt vmcnt(0) lgkmcnt(0)
	s_waitcnt lgkmcnt(0)
	v_add_u32_e32 v0, s84, v0
	v_cmp_gt_u32_e32 vcc, 64, v0
	s_barrier
	s_and_saveexec_b64 s[0:1], vcc
	s_cbranch_execz .LBB0_790
	s_waitcnt vmcnt(0)
	s_waitcnt vmcnt(0)
	v_cmp_eq_u32_e32 vcc, 0, v0
	s_and_saveexec_b64 s[2:3], vcc
	s_cbranch_execz .LBB0_789
	s_sub_i32 s4, 21, s34
	s_getreg_b32 s5, hwreg(HW_REG_XCC_ID, 0, 4)
	s_mul_i32 s6, s98, s4
	s_lshl_b32 s5, s5, 8
	v_mov_b32_e32 v0, s5
	v_mov_b32_e32 v1, 1
	global_atomic_add v1, v0, v1, s[68:69] sc0
	s_mul_i32 s7, s101, s4
	s_add_u32 s5, s5, 0x1080
	s_waitcnt vmcnt(0)
	v_add_u32_e32 v1, 1, v1
	v_cmp_eq_u32_e32 vcc, s6, v1
	s_cbranch_vccz .Lgb_half_s20
	buffer_wbl2 sc1
	s_waitcnt vmcnt(0)
	v_mov_b32_e32 v0, 0
	v_mov_b32_e32 v1, 1
	global_atomic_add v1, v0, v1, s[14:15] sc0
	buffer_inv sc1
	s_waitcnt vmcnt(1)
	v_add_u32_e32 v1, 1, v1
	v_cmp_eq_u32_e32 vcc, s7, v1
	s_cbranch_vccnz .Lgb_rel_s20
